# NSA mode-2: per-wave skip of fully masked tiles (single-tile and DMA-only paths), fast loop tail
# speedup vs baseline: 1.0339x; 1.0139x over previous
.LBB0_1463:
	s_cmp_eq_u32 s63, 2
	s_cbranch_scc0 .Lm2_no
	s_add_i32 s98, s54, 1
	s_cmp_ge_i32 s98, s53
	s_cbranch_scc1 .Lm2_no
	v_cmp_eq_f32_e64 s[18:19], s73, v222
	s_cmp_lg_u64 s[18:19], 0
	s_cbranch_scc1 .Lm2_no
	s_add_i32 s21, s38, s45
	s_and_b32 s20, s45, 2
	s_add_i32 s54, s54, 1
	s_mov_b64 s[94:95], 0
	s_lshl_b32 s30, s20, 13
	v_add_u32_e32 v8, s30, v169
	v_add_u32_e32 v3, s30, v193
	s_lshr_b32 s0, s21, 5
	s_cmp_lt_u32 s0, 2
	s_cselect_b64 s[98:99], -1, 0
	s_bitcmp1_b32 s0, 0
	s_cselect_b64 s[0:1], -1, 0
	s_and_b32 s28, s21, 31
	v_cndmask_b32_e64 v5, v130, v131, s[0:1]
	v_cndmask_b32_e64 v6, v132, v133, s[0:1]
	v_cndmask_b32_e64 v5, v6, v5, s[98:99]
	v_lshrrev_b32_e32 v5, s28, v5
	v_and_b32_e32 v6, 1, v5
	v_bfe_u32 v9, v5, 1, 1
	v_xor_b32_e32 v7, 0x80000000, v222
	v_cmp_eq_u32_e32 vcc, 1, v6
	v_cmp_eq_u32_e64 s[98:99], 1, v9
	v_add_f32_e32 v4, v7, v201
	s_cmp_lg_u64 vcc, 0
	s_cselect_b32 s55, 1, 0
	v_cndmask_b32_e32 v82, v4, v7, vcc
	v_cndmask_b32_e64 v50, v4, v7, s[98:99]
	s_cmp_lg_u64 s[98:99], 0
	s_cselect_b32 s0, 2, 0
	s_or_b32 s55, s55, s0
	s_cmp_eq_u32 s55, 3
	s_cbranch_scc0 .Lm2_partial
	ds_read_b128 v[10:13], v8
	ds_read_b128 v[14:17], v8 offset:512
	ds_read_b128 v[174:177], v8 offset:2048
	ds_read_b128 v[178:181], v8 offset:2560
	ds_read_b128 v[182:185], v8 offset:4096
	ds_read_b128 v[186:189], v8 offset:4608
	ds_read_b128 v[228:231], v8 offset:6144
	ds_read_b128 v[232:235], v8 offset:6656
	v_mov_b32_e32 v83, v82
	v_mov_b64_e32 v[84:85], v[82:83]
	v_mov_b64_e32 v[86:87], v[82:83]
	v_mov_b64_e32 v[88:89], v[82:83]
	v_mov_b64_e32 v[90:91], v[82:83]
	v_mov_b64_e32 v[92:93], v[82:83]
	v_mov_b64_e32 v[94:95], v[82:83]
	v_mov_b64_e32 v[96:97], v[82:83]
	v_mov_b32_e32 v51, v50
	v_mov_b64_e32 v[52:53], v[50:51]
	s_waitcnt lgkmcnt(7)
	v_mfma_f32_32x32x16_bf16 v[98:113], v[10:13], v[114:117], v[82:97]
	ds_read_b128 v[10:13], v8 offset:8192
	v_mov_b64_e32 v[54:55], v[50:51]
	v_mov_b64_e32 v[56:57], v[50:51]
	v_mov_b64_e32 v[58:59], v[50:51]
	v_mov_b64_e32 v[60:61], v[50:51]
	v_mov_b64_e32 v[62:63], v[50:51]
	v_mov_b64_e32 v[64:65], v[50:51]
	s_add_i32 s0, s21, 2
	s_ashr_i32 s1, s0, 31
	s_lshl_b64 s[0:1], s[0:1], 6
	s_add_u32 s0, s0, s84
	s_waitcnt lgkmcnt(7)
	v_mfma_f32_32x32x16_bf16 v[82:97], v[14:17], v[114:117], v[82:97]
	ds_read_b128 v[14:17], v8 offset:8704
	s_addc_u32 s1, s1, s85
	s_lshl_b64 s[0:1], s[0:1], 7
	s_add_u32 s28, s86, s0
	s_addc_u32 s29, s87, s1
	s_sub_i32 s31, s37, s30
	s_add_i32 s31, s31, 0x4000
	v_lshlrev_b32_e32 v5, 7, v138
	s_mov_b32 m0, s31
	s_movk_i32 s30, 0x80
	global_load_lds_dwordx4 v5, s[28:29]
	s_waitcnt lgkmcnt(7)
	v_mfma_f32_32x32x16_bf16 v[98:113], v[174:177], v[118:121], v[98:113]
	ds_read_b128 v[174:177], v8 offset:10240
	v_mad_u64_u32 v[226:227], vcc, v168, s30, v[134:135]
	s_add_i32 s31, s31, 0x8000
	v_lshl_add_u64 v[6:7], v[226:227], 0, s[0:1]
	s_mov_b32 m0, s31
	s_cmp_lt_i32 s45, s44
	global_load_lds_dwordx4 v[6:7], off
	s_cselect_b32 s98, 0x2000, 0
	s_add_u32 s28, s28, s98
	s_waitcnt lgkmcnt(7)
	v_mfma_f32_32x32x16_bf16 v[82:97], v[178:181], v[118:121], v[82:97]
	ds_read_b128 v[178:181], v8 offset:10752
	s_addc_u32 s29, s29, 0
	s_add_u32 s0, s0, s98
	s_addc_u32 s1, s1, 0
	s_sub_i32 s31, s31, 0x6000
	s_mov_b32 m0, s31
	v_lshl_add_u64 v[6:7], v[226:227], 0, s[0:1]
	global_load_lds_dwordx4 v5, s[28:29]
	s_add_i32 s31, s31, 0x8000
	s_waitcnt lgkmcnt(7)
	v_mfma_f32_32x32x16_bf16 v[98:113], v[182:185], v[122:125], v[98:113]
	ds_read_b128 v[182:185], v8 offset:12288
	s_mov_b32 m0, s31
	s_nop 0
	global_load_lds_dwordx4 v[6:7], off
	s_waitcnt lgkmcnt(7)
	v_mfma_f32_32x32x16_bf16 v[82:97], v[186:189], v[122:125], v[82:97]
	ds_read_b128 v[186:189], v8 offset:12800
	s_waitcnt lgkmcnt(7)
	v_mfma_f32_32x32x16_bf16 v[98:113], v[228:231], v[126:129], v[98:113]
	ds_read_b128 v[228:231], v8 offset:14336
	s_waitcnt lgkmcnt(7)
	v_mfma_f32_32x32x16_bf16 v[82:97], v[232:235], v[126:129], v[82:97]
	ds_read_b128 v[232:235], v8 offset:14848
	s_waitcnt lgkmcnt(7)
	v_mfma_f32_32x32x16_bf16 v[66:81], v[10:13], v[114:117], v[50:65]
	ds_read_b64_tr_b16 v[10:11], v3 offset:32768
	ds_read_b64_tr_b16 v[12:13], v3 offset:33280
	s_waitcnt lgkmcnt(8)
	v_mfma_f32_32x32x16_bf16 v[50:65], v[14:17], v[114:117], v[50:65]
	ds_read_b64_tr_b16 v[14:15], v3 offset:36864
	ds_read_b64_tr_b16 v[16:17], v3 offset:37376
	s_waitcnt lgkmcnt(9)
	v_mfma_f32_32x32x16_bf16 v[66:81], v[174:177], v[118:121], v[66:81]
	ds_read_b64_tr_b16 v[174:175], v3 offset:33792
	ds_read_b64_tr_b16 v[176:177], v3 offset:34304
	v_exp_f32_e32 v98, v98
	v_exp_f32_e32 v99, v99
	v_exp_f32_e32 v100, v100
	v_exp_f32_e32 v101, v101
	v_exp_f32_e32 v102, v102
	s_waitcnt lgkmcnt(10)
	v_mfma_f32_32x32x16_bf16 v[50:65], v[178:181], v[118:121], v[50:65]
	ds_read_b64_tr_b16 v[178:179], v3 offset:37888
	ds_read_b64_tr_b16 v[180:181], v3 offset:38400
	v_exp_f32_e32 v103, v103
	v_exp_f32_e32 v104, v104
	v_exp_f32_e32 v105, v105
	v_cvt_pk_bf16_f32 v236, v98, v99
	v_cvt_pk_bf16_f32 v237, v100, v101
	v_cvt_pk_bf16_f32 v238, v102, v103
	v_cvt_pk_bf16_f32 v239, v104, v105
	s_waitcnt lgkmcnt(11)
	v_mfma_f32_32x32x16_bf16 v[66:81], v[182:185], v[122:125], v[66:81]
	ds_read_b64_tr_b16 v[182:183], v3 offset:34816
	ds_read_b64_tr_b16 v[184:185], v3 offset:35328
	v_exp_f32_e32 v106, v106
	v_exp_f32_e32 v107, v107
	v_exp_f32_e32 v108, v108
	v_exp_f32_e32 v109, v109
	v_exp_f32_e32 v110, v110
	s_waitcnt lgkmcnt(12)
	v_mfma_f32_32x32x16_bf16 v[50:65], v[186:189], v[122:125], v[50:65]
	ds_read_b64_tr_b16 v[186:187], v3 offset:38912
	ds_read_b64_tr_b16 v[188:189], v3 offset:39424
	v_exp_f32_e32 v111, v111
	v_exp_f32_e32 v112, v112
	v_exp_f32_e32 v113, v113
	v_cvt_pk_bf16_f32 v240, v106, v107
	v_cvt_pk_bf16_f32 v241, v108, v109
	v_cvt_pk_bf16_f32 v242, v110, v111
	v_cvt_pk_bf16_f32 v243, v112, v113
	s_waitcnt lgkmcnt(13)
	v_mfma_f32_32x32x16_bf16 v[66:81], v[228:231], v[126:129], v[66:81]
	ds_read_b64_tr_b16 v[228:229], v3 offset:35840
	ds_read_b64_tr_b16 v[230:231], v3 offset:36352
	v_exp_f32_e32 v82, v82
	v_exp_f32_e32 v83, v83
	v_exp_f32_e32 v84, v84
	v_exp_f32_e32 v85, v85
	v_exp_f32_e32 v86, v86
	s_waitcnt lgkmcnt(14)
	v_mfma_f32_32x32x16_bf16 v[50:65], v[232:235], v[126:129], v[50:65]
	s_waitcnt lgkmcnt(13)
	ds_read_b64_tr_b16 v[232:233], v3 offset:39936
	ds_read_b64_tr_b16 v[234:235], v3 offset:40448
	v_exp_f32_e32 v87, v87
	v_exp_f32_e32 v88, v88
	v_exp_f32_e32 v89, v89
	v_cvt_pk_bf16_f32 v244, v82, v83
	v_cvt_pk_bf16_f32 v245, v84, v85
	v_cvt_pk_bf16_f32 v246, v86, v87
	v_cvt_pk_bf16_f32 v247, v88, v89
	s_waitcnt lgkmcnt(14)
	v_mfma_f32_32x32x16_bf16 v[34:49], v[236:239], v[10:13], v[34:49]
	s_waitcnt lgkmcnt(13)
	ds_read_b64_tr_b16 v[10:11], v3 offset:40960
	ds_read_b64_tr_b16 v[12:13], v3 offset:41472
	v_exp_f32_e32 v90, v90
	v_exp_f32_e32 v91, v91
	v_exp_f32_e32 v92, v92
	v_exp_f32_e32 v93, v93
	v_exp_f32_e32 v94, v94
	s_waitcnt lgkmcnt(14)
	v_mfma_f32_32x32x16_bf16 v[18:33], v[236:239], v[14:17], v[18:33]
	s_waitcnt lgkmcnt(13)
	ds_read_b64_tr_b16 v[14:15], v3 offset:45056
	ds_read_b64_tr_b16 v[16:17], v3 offset:45568
	v_exp_f32_e32 v95, v95
	v_exp_f32_e32 v96, v96
	v_exp_f32_e32 v97, v97
	v_cvt_pk_bf16_f32 v248, v90, v91
	v_cvt_pk_bf16_f32 v249, v92, v93
	v_cvt_pk_bf16_f32 v250, v94, v95
	v_cvt_pk_bf16_f32 v251, v96, v97
	s_waitcnt lgkmcnt(14)
	v_mfma_f32_32x32x16_bf16 v[34:49], v[240:243], v[174:177], v[34:49]
	s_waitcnt lgkmcnt(13)
	ds_read_b64_tr_b16 v[174:175], v3 offset:41984
	ds_read_b64_tr_b16 v[176:177], v3 offset:42496
	v_exp_f32_e32 v66, v66
	v_exp_f32_e32 v67, v67
	v_exp_f32_e32 v68, v68
	v_exp_f32_e32 v69, v69
	v_exp_f32_e32 v70, v70
	s_waitcnt lgkmcnt(14)
	v_mfma_f32_32x32x16_bf16 v[18:33], v[240:243], v[178:181], v[18:33]
	s_waitcnt lgkmcnt(13)
	ds_read_b64_tr_b16 v[178:179], v3 offset:46080
	ds_read_b64_tr_b16 v[180:181], v3 offset:46592
	v_exp_f32_e32 v71, v71
	v_exp_f32_e32 v72, v72
	v_exp_f32_e32 v73, v73
	v_cvt_pk_bf16_f32 v236, v66, v67
	v_cvt_pk_bf16_f32 v237, v68, v69
	v_cvt_pk_bf16_f32 v238, v70, v71
	v_cvt_pk_bf16_f32 v239, v72, v73
	s_waitcnt lgkmcnt(14)
	v_mfma_f32_32x32x16_bf16 v[34:49], v[244:247], v[182:185], v[34:49]
	s_waitcnt lgkmcnt(13)
	ds_read_b64_tr_b16 v[182:183], v3 offset:43008
	ds_read_b64_tr_b16 v[184:185], v3 offset:43520
	v_exp_f32_e32 v74, v74
	v_exp_f32_e32 v75, v75
	v_exp_f32_e32 v76, v76
	v_exp_f32_e32 v77, v77
	v_exp_f32_e32 v78, v78
	s_waitcnt lgkmcnt(14)
	v_mfma_f32_32x32x16_bf16 v[18:33], v[244:247], v[186:189], v[18:33]
	s_waitcnt lgkmcnt(13)
	ds_read_b64_tr_b16 v[186:187], v3 offset:47104
	ds_read_b64_tr_b16 v[188:189], v3 offset:47616
	v_exp_f32_e32 v79, v79
	v_exp_f32_e32 v80, v80
	v_exp_f32_e32 v81, v81
	v_cvt_pk_bf16_f32 v240, v74, v75
	v_cvt_pk_bf16_f32 v241, v76, v77
	v_cvt_pk_bf16_f32 v242, v78, v79
	v_cvt_pk_bf16_f32 v243, v80, v81
	s_waitcnt lgkmcnt(14)
	v_mfma_f32_32x32x16_bf16 v[34:49], v[248:251], v[228:231], v[34:49]
	s_waitcnt lgkmcnt(13)
	ds_read_b64_tr_b16 v[228:229], v3 offset:44032
	ds_read_b64_tr_b16 v[230:231], v3 offset:44544
	v_exp_f32_e32 v50, v50
	v_exp_f32_e32 v51, v51
	v_exp_f32_e32 v52, v52
	v_exp_f32_e32 v53, v53
	v_exp_f32_e32 v54, v54
	s_waitcnt lgkmcnt(14)
	v_mfma_f32_32x32x16_bf16 v[18:33], v[248:251], v[232:235], v[18:33]
	s_waitcnt lgkmcnt(13)
	ds_read_b64_tr_b16 v[232:233], v3 offset:48128
	ds_read_b64_tr_b16 v[234:235], v3 offset:48640
	v_exp_f32_e32 v55, v55
	v_exp_f32_e32 v56, v56
	v_exp_f32_e32 v57, v57
	v_cvt_pk_bf16_f32 v244, v50, v51
	v_cvt_pk_bf16_f32 v245, v52, v53
	v_cvt_pk_bf16_f32 v246, v54, v55
	v_cvt_pk_bf16_f32 v247, v56, v57
	s_waitcnt lgkmcnt(14)
	v_mfma_f32_32x32x16_bf16 v[34:49], v[236:239], v[10:13], v[34:49]
	v_exp_f32_e32 v58, v58
	v_exp_f32_e32 v59, v59
	v_exp_f32_e32 v60, v60
	v_exp_f32_e32 v61, v61
	v_exp_f32_e32 v62, v62
	s_waitcnt lgkmcnt(12)
	v_mfma_f32_32x32x16_bf16 v[18:33], v[236:239], v[14:17], v[18:33]
	v_exp_f32_e32 v63, v63
	v_exp_f32_e32 v64, v64
	v_exp_f32_e32 v65, v65
	v_cvt_pk_bf16_f32 v248, v58, v59
	v_cvt_pk_bf16_f32 v249, v60, v61
	v_cvt_pk_bf16_f32 v250, v62, v63
	v_cvt_pk_bf16_f32 v251, v64, v65
	s_waitcnt lgkmcnt(10)
	v_mfma_f32_32x32x16_bf16 v[34:49], v[240:243], v[174:177], v[34:49]
	v_pk_add_f32 v[4:5], v[98:99], v[100:101]
	v_pk_add_f32 v[6:7], v[82:83], v[84:85]
	v_pk_add_f32 v[4:5], v[4:5], v[102:103]
	v_pk_add_f32 v[6:7], v[6:7], v[86:87]
	v_pk_add_f32 v[4:5], v[4:5], v[104:105]
	v_pk_add_f32 v[6:7], v[6:7], v[88:89]
	v_pk_add_f32 v[4:5], v[4:5], v[106:107]
	v_pk_add_f32 v[6:7], v[6:7], v[90:91]
	v_pk_add_f32 v[4:5], v[4:5], v[108:109]
	v_pk_add_f32 v[6:7], v[6:7], v[92:93]
	s_waitcnt lgkmcnt(8)
	v_mfma_f32_32x32x16_bf16 v[18:33], v[240:243], v[178:181], v[18:33]
	v_pk_add_f32 v[4:5], v[4:5], v[110:111]
	v_pk_add_f32 v[6:7], v[6:7], v[94:95]
	v_pk_add_f32 v[4:5], v[4:5], v[112:113]
	v_pk_add_f32 v[6:7], v[6:7], v[96:97]
	v_add_f32_e32 v6, v6, v7
	v_add_f32_e32 v4, v4, v5
	v_add_f32_e32 v4, v6, v4
	v_mov_b32_e32 v5, v4
	v_add_f32_e32 v225, v225, v4
	v_pk_add_f32 v[4:5], v[66:67], v[68:69]
	s_waitcnt lgkmcnt(6)
	v_mfma_f32_32x32x16_bf16 v[34:49], v[244:247], v[182:185], v[34:49]
	v_pk_add_f32 v[6:7], v[50:51], v[52:53]
	v_pk_add_f32 v[4:5], v[4:5], v[70:71]
	v_pk_add_f32 v[6:7], v[6:7], v[54:55]
	v_pk_add_f32 v[4:5], v[4:5], v[72:73]
	v_pk_add_f32 v[6:7], v[6:7], v[56:57]
	v_pk_add_f32 v[4:5], v[4:5], v[74:75]
	v_pk_add_f32 v[6:7], v[6:7], v[58:59]
	v_pk_add_f32 v[4:5], v[4:5], v[76:77]
	v_pk_add_f32 v[6:7], v[6:7], v[60:61]
	v_pk_add_f32 v[4:5], v[4:5], v[78:79]
	s_waitcnt lgkmcnt(4)
	v_mfma_f32_32x32x16_bf16 v[18:33], v[244:247], v[186:189], v[18:33]
	v_pk_add_f32 v[6:7], v[6:7], v[62:63]
	v_pk_add_f32 v[4:5], v[4:5], v[80:81]
	v_pk_add_f32 v[6:7], v[6:7], v[64:65]
	v_add_f32_e32 v6, v6, v7
	v_add_f32_e32 v4, v4, v5
	v_add_f32_e32 v4, v6, v4
	v_add_f32_e32 v225, v225, v4
	s_mov_b64 s[20:21], 0
	s_waitcnt lgkmcnt(2)
	v_mfma_f32_32x32x16_bf16 v[34:49], v[248:251], v[228:231], v[34:49]
	s_waitcnt lgkmcnt(0)
	v_mfma_f32_32x32x16_bf16 v[18:33], v[248:251], v[232:235], v[18:33]
	s_mov_b32 s30, 0x437f0000
	v_cmp_nge_f32_e32 vcc, s30, v5
	v_cmp_nge_f32_e64 s[98:99], s30, v4
	s_or_b64 s[98:99], vcc, s[98:99]
	s_cbranch_scc1 .Lm2_rare_full
	s_waitcnt vmcnt(0) lgkmcnt(0)
	s_barrier
	s_add_i32 s45, s45, 2
	s_branch .LBB0_1463
.Lm2_rare_full:
	v_max3_f32 v5, v98, v99, v100
	v_max3_f32 v6, v106, v107, v108
	v_max3_f32 v9, v82, v83, v84
	v_max3_f32 v227, v90, v91, v92
	v_max3_f32 v5, v5, v101, v102
	v_max3_f32 v6, v6, v109, v110
	v_max3_f32 v9, v9, v85, v86
	v_max3_f32 v227, v227, v93, v94
	v_max3_f32 v5, v5, v103, v104
	v_max3_f32 v6, v6, v111, v112
	v_max3_f32 v9, v9, v87, v88
	v_max3_f32 v227, v227, v95, v96
	v_max3_f32 v5, v5, v105, v113
	v_max3_f32 v9, v9, v89, v97
	v_max3_f32 v5, v5, v6, v9
	v_max_f32_e32 v5, v5, v227
	v_mov_b32_e32 v6, v5
	s_nop 1
	v_permlane32_swap_b32_e32 v5, v6
	v_max_f32_e32 v5, v5, v6
	v_log_f32_e32 v5, v5
	s_nop 0
	v_cmp_lt_f32_e32 vcc, s74, v5
	s_and_b64 s[28:29], s[18:19], vcc
	v_cmp_lt_f32_e32 vcc, s75, v5
	s_or_b64 s[28:29], vcc, s[28:29]
	s_nop 0
	v_cndmask_b32_e64 v252, 0, v5, s[28:29]
	s_cselect_b64 s[28:29], -1, 0
	v_max3_f32 v5, v66, v67, v68
	v_max3_f32 v6, v74, v75, v76
	v_max3_f32 v9, v50, v51, v52
	v_max3_f32 v227, v58, v59, v60
	v_max3_f32 v5, v5, v69, v70
	v_max3_f32 v6, v6, v77, v78
	v_max3_f32 v9, v9, v53, v54
	v_max3_f32 v227, v227, v61, v62
	v_max3_f32 v5, v5, v71, v72
	v_max3_f32 v6, v6, v79, v80
	v_max3_f32 v9, v9, v55, v56
	v_max3_f32 v227, v227, v63, v64
	v_max3_f32 v5, v5, v73, v81
	v_max3_f32 v9, v9, v57, v65
	v_max3_f32 v5, v5, v6, v9
	v_max_f32_e32 v5, v5, v227
	v_mov_b32_e32 v6, v5
	s_nop 1
	v_permlane32_swap_b32_e32 v5, v6
	v_max_f32_e32 v5, v5, v6
	v_log_f32_e32 v5, v5
	s_nop 0
	v_cmp_lt_f32_e32 vcc, s74, v5
	s_and_b64 s[0:1], s[18:19], vcc
	v_cmp_lt_f32_e32 vcc, s75, v5
	s_or_b64 s[0:1], vcc, s[0:1]
	s_nop 0
	v_cndmask_b32_e64 v101, 0, v5, s[0:1]
	s_cselect_b64 s[0:1], -1, 0
	v_mov_b32_e32 v228, v252
	s_branch .LBB0_1492
.Lm2_partial:
	s_cmp_eq_u32 s55, 0
	s_cbranch_scc1 .Lm2_none
	s_cmp_eq_u32 s55, 2
	s_cbranch_scc0 .Lm2_st
	v_add_u32_e32 v8, 0x2000, v8
	v_add_u32_e32 v3, 0x2000, v3
	v_mov_b32_e32 v82, v50
.Lm2_st:
	ds_read_b128 v[10:13], v8
	ds_read_b128 v[14:17], v8 offset:512
	ds_read_b128 v[174:177], v8 offset:2048
	ds_read_b128 v[178:181], v8 offset:2560
	ds_read_b128 v[182:185], v8 offset:4096
	ds_read_b128 v[186:189], v8 offset:4608
	ds_read_b128 v[228:231], v8 offset:6144
	ds_read_b128 v[232:235], v8 offset:6656
	v_mov_b32_e32 v83, v82
	v_mov_b64_e32 v[84:85], v[82:83]
	v_mov_b64_e32 v[86:87], v[82:83]
	v_mov_b64_e32 v[88:89], v[82:83]
	v_mov_b64_e32 v[90:91], v[82:83]
	v_mov_b64_e32 v[92:93], v[82:83]
	v_mov_b64_e32 v[94:95], v[82:83]
	v_mov_b64_e32 v[96:97], v[82:83]
	s_add_i32 s0, s21, 2
	s_ashr_i32 s1, s0, 31
	s_waitcnt lgkmcnt(7)
	v_mfma_f32_32x32x16_bf16 v[98:113], v[10:13], v[114:117], v[82:97]
	ds_read_b64_tr_b16 v[10:11], v3 offset:32768
	ds_read_b64_tr_b16 v[12:13], v3 offset:33280
	s_lshl_b64 s[0:1], s[0:1], 6
	s_add_u32 s0, s0, s84
	s_addc_u32 s1, s1, s85
	s_lshl_b64 s[0:1], s[0:1], 7
	s_add_u32 s28, s86, s0
	s_addc_u32 s29, s87, s1
	s_sub_i32 s31, s37, s30
	s_add_i32 s31, s31, 0x4000
	v_lshlrev_b32_e32 v5, 7, v138
	s_mov_b32 m0, s31
	s_waitcnt lgkmcnt(8)
	v_mfma_f32_32x32x16_bf16 v[82:97], v[14:17], v[114:117], v[82:97]
	ds_read_b64_tr_b16 v[14:15], v3 offset:36864
	ds_read_b64_tr_b16 v[16:17], v3 offset:37376
	s_movk_i32 s30, 0x80
	global_load_lds_dwordx4 v5, s[28:29]
	v_mad_u64_u32 v[226:227], vcc, v168, s30, v[134:135]
	s_add_i32 s31, s31, 0x8000
	v_lshl_add_u64 v[6:7], v[226:227], 0, s[0:1]
	s_mov_b32 m0, s31
	s_cmp_lt_i32 s45, s44
	global_load_lds_dwordx4 v[6:7], off
	s_waitcnt lgkmcnt(9)
	v_mfma_f32_32x32x16_bf16 v[98:113], v[174:177], v[118:121], v[98:113]
	ds_read_b64_tr_b16 v[174:175], v3 offset:33792
	ds_read_b64_tr_b16 v[176:177], v3 offset:34304
	s_cselect_b32 s98, 0x2000, 0
	s_add_u32 s28, s28, s98
	s_addc_u32 s29, s29, 0
	s_add_u32 s0, s0, s98
	s_addc_u32 s1, s1, 0
	s_sub_i32 s31, s31, 0x6000
	s_mov_b32 m0, s31
	v_lshl_add_u64 v[6:7], v[226:227], 0, s[0:1]
	global_load_lds_dwordx4 v5, s[28:29]
	s_waitcnt lgkmcnt(10)
	v_mfma_f32_32x32x16_bf16 v[82:97], v[178:181], v[118:121], v[82:97]
	ds_read_b64_tr_b16 v[178:179], v3 offset:37888
	ds_read_b64_tr_b16 v[180:181], v3 offset:38400
	s_add_i32 s31, s31, 0x8000
	s_mov_b32 m0, s31
	s_nop 0
	global_load_lds_dwordx4 v[6:7], off
	s_waitcnt lgkmcnt(11)
	v_mfma_f32_32x32x16_bf16 v[98:113], v[182:185], v[122:125], v[98:113]
	ds_read_b64_tr_b16 v[182:183], v3 offset:34816
	ds_read_b64_tr_b16 v[184:185], v3 offset:35328
	s_waitcnt lgkmcnt(12)
	v_mfma_f32_32x32x16_bf16 v[82:97], v[186:189], v[122:125], v[82:97]
	ds_read_b64_tr_b16 v[186:187], v3 offset:38912
	ds_read_b64_tr_b16 v[188:189], v3 offset:39424
	s_waitcnt lgkmcnt(13)
	v_mfma_f32_32x32x16_bf16 v[98:113], v[228:231], v[126:129], v[98:113]
	ds_read_b64_tr_b16 v[228:229], v3 offset:35840
	ds_read_b64_tr_b16 v[230:231], v3 offset:36352
	s_waitcnt lgkmcnt(14)
	v_mfma_f32_32x32x16_bf16 v[82:97], v[232:235], v[126:129], v[82:97]
	s_waitcnt lgkmcnt(13)
	ds_read_b64_tr_b16 v[232:233], v3 offset:39936
	ds_read_b64_tr_b16 v[234:235], v3 offset:40448
	s_nop 0
	s_nop 0
	s_nop 0
	s_nop 0
	s_nop 0
	s_nop 0
	s_nop 0
	s_nop 0
	s_nop 0
	v_exp_f32_e32 v98, v98
	v_exp_f32_e32 v99, v99
	v_exp_f32_e32 v100, v100
	v_exp_f32_e32 v101, v101
	v_exp_f32_e32 v102, v102
	v_exp_f32_e32 v103, v103
	v_exp_f32_e32 v104, v104
	v_exp_f32_e32 v105, v105
	v_cvt_pk_bf16_f32 v236, v98, v99
	v_cvt_pk_bf16_f32 v237, v100, v101
	v_cvt_pk_bf16_f32 v238, v102, v103
	v_cvt_pk_bf16_f32 v239, v104, v105
	v_exp_f32_e32 v106, v106
	v_exp_f32_e32 v107, v107
	s_waitcnt lgkmcnt(14)
	v_mfma_f32_32x32x16_bf16 v[34:49], v[236:239], v[10:13], v[34:49]
	v_exp_f32_e32 v108, v108
	v_exp_f32_e32 v109, v109
	v_exp_f32_e32 v110, v110
	v_exp_f32_e32 v111, v111
	v_exp_f32_e32 v112, v112
	s_waitcnt lgkmcnt(12)
	v_mfma_f32_32x32x16_bf16 v[18:33], v[236:239], v[14:17], v[18:33]
	v_exp_f32_e32 v113, v113
	v_cvt_pk_bf16_f32 v240, v106, v107
	v_cvt_pk_bf16_f32 v241, v108, v109
	v_cvt_pk_bf16_f32 v242, v110, v111
	v_cvt_pk_bf16_f32 v243, v112, v113
	v_exp_f32_e32 v82, v82
	v_exp_f32_e32 v83, v83
	s_waitcnt lgkmcnt(10)
	v_mfma_f32_32x32x16_bf16 v[34:49], v[240:243], v[174:177], v[34:49]
	v_exp_f32_e32 v84, v84
	v_exp_f32_e32 v85, v85
	v_exp_f32_e32 v86, v86
	v_exp_f32_e32 v87, v87
	v_exp_f32_e32 v88, v88
	s_waitcnt lgkmcnt(8)
	v_mfma_f32_32x32x16_bf16 v[18:33], v[240:243], v[178:181], v[18:33]
	v_exp_f32_e32 v89, v89
	v_cvt_pk_bf16_f32 v244, v82, v83
	v_cvt_pk_bf16_f32 v245, v84, v85
	v_cvt_pk_bf16_f32 v246, v86, v87
	v_cvt_pk_bf16_f32 v247, v88, v89
	v_exp_f32_e32 v90, v90
	v_exp_f32_e32 v91, v91
	s_waitcnt lgkmcnt(6)
	v_mfma_f32_32x32x16_bf16 v[34:49], v[244:247], v[182:185], v[34:49]
	v_exp_f32_e32 v92, v92
	v_exp_f32_e32 v93, v93
	v_exp_f32_e32 v94, v94
	v_exp_f32_e32 v95, v95
	v_exp_f32_e32 v96, v96
	s_waitcnt lgkmcnt(4)
	v_mfma_f32_32x32x16_bf16 v[18:33], v[244:247], v[186:189], v[18:33]
	v_exp_f32_e32 v97, v97
	v_cvt_pk_bf16_f32 v248, v90, v91
	v_cvt_pk_bf16_f32 v249, v92, v93
	v_cvt_pk_bf16_f32 v250, v94, v95
	v_cvt_pk_bf16_f32 v251, v96, v97
	v_pk_add_f32 v[4:5], v[98:99], v[100:101]
	v_pk_add_f32 v[6:7], v[82:83], v[84:85]
	v_pk_add_f32 v[4:5], v[4:5], v[102:103]
	v_pk_add_f32 v[6:7], v[6:7], v[86:87]
	s_waitcnt lgkmcnt(2)
	v_mfma_f32_32x32x16_bf16 v[34:49], v[248:251], v[228:231], v[34:49]
	v_pk_add_f32 v[4:5], v[4:5], v[104:105]
	v_pk_add_f32 v[6:7], v[6:7], v[88:89]
	v_pk_add_f32 v[4:5], v[4:5], v[106:107]
	v_pk_add_f32 v[6:7], v[6:7], v[90:91]
	v_pk_add_f32 v[4:5], v[4:5], v[108:109]
	v_pk_add_f32 v[6:7], v[6:7], v[92:93]
	v_pk_add_f32 v[4:5], v[4:5], v[110:111]
	v_pk_add_f32 v[6:7], v[6:7], v[94:95]
	v_pk_add_f32 v[4:5], v[4:5], v[112:113]
	v_pk_add_f32 v[6:7], v[6:7], v[96:97]
	s_waitcnt lgkmcnt(0)
	v_mfma_f32_32x32x16_bf16 v[18:33], v[248:251], v[232:235], v[18:33]
	v_add_f32_e32 v6, v6, v7
	v_add_f32_e32 v4, v4, v5
	v_add_f32_e32 v4, v6, v4
	v_mov_b32_e32 v5, v4
	v_add_f32_e32 v225, v225, v4
	s_mov_b64 s[20:21], 0
	s_mov_b32 s30, 0x437f0000
	v_cmp_nge_f32_e32 vcc, s30, v5
	s_cmp_lg_u64 vcc, 0
	s_cbranch_scc1 .Lm2_rare_st
	s_waitcnt vmcnt(0) lgkmcnt(0)
	s_barrier
	s_add_i32 s45, s45, 2
	s_branch .LBB0_1463
.Lm2_rare_st:
	v_max3_f32 v5, v98, v99, v100
	v_max3_f32 v6, v106, v107, v108
	v_max3_f32 v9, v82, v83, v84
	v_max3_f32 v227, v90, v91, v92
	v_max3_f32 v5, v5, v101, v102
	v_max3_f32 v6, v6, v109, v110
	v_max3_f32 v9, v9, v85, v86
	v_max3_f32 v227, v227, v93, v94
	v_max3_f32 v5, v5, v103, v104
	v_max3_f32 v6, v6, v111, v112
	v_max3_f32 v9, v9, v87, v88
	v_max3_f32 v227, v227, v95, v96
	v_max3_f32 v5, v5, v105, v113
	v_max3_f32 v9, v9, v89, v97
	v_max3_f32 v5, v5, v6, v9
	v_max_f32_e32 v5, v5, v227
	v_mov_b32_e32 v6, v5
	s_nop 1
	v_permlane32_swap_b32_e32 v5, v6
	v_max_f32_e32 v5, v5, v6
	v_log_f32_e32 v5, v5
	s_nop 0
	v_cmp_lt_f32_e32 vcc, s74, v5
	s_and_b64 s[28:29], s[18:19], vcc
	v_cmp_lt_f32_e32 vcc, s75, v5
	s_or_b64 s[28:29], vcc, s[28:29]
	s_nop 0
	v_cndmask_b32_e64 v252, 0, v5, s[28:29]
	s_cselect_b64 s[28:29], -1, 0
	v_mov_b32_e32 v101, 0
	s_mov_b64 s[0:1], 0
	v_mov_b32_e32 v228, v252
	s_branch .LBB0_1492
.Lm2_none:
	s_add_i32 s0, s21, 2
	s_ashr_i32 s1, s0, 31
	s_lshl_b64 s[0:1], s[0:1], 6
	s_add_u32 s0, s0, s84
	s_addc_u32 s1, s1, s85
	s_lshl_b64 s[0:1], s[0:1], 7
	s_add_u32 s28, s86, s0
	s_addc_u32 s29, s87, s1
	s_sub_i32 s31, s37, s30
	s_add_i32 s31, s31, 0x4000
	v_lshlrev_b32_e32 v5, 7, v138
	s_mov_b32 m0, s31
	s_movk_i32 s30, 0x80
	global_load_lds_dwordx4 v5, s[28:29]
	v_mad_u64_u32 v[226:227], vcc, v168, s30, v[134:135]
	s_add_i32 s31, s31, 0x8000
	v_lshl_add_u64 v[6:7], v[226:227], 0, s[0:1]
	s_mov_b32 m0, s31
	s_cmp_lt_i32 s45, s44
	global_load_lds_dwordx4 v[6:7], off
	s_cselect_b32 s98, 0x2000, 0
	s_add_u32 s28, s28, s98
	s_addc_u32 s29, s29, 0
	s_add_u32 s0, s0, s98
	s_addc_u32 s1, s1, 0
	s_sub_i32 s31, s31, 0x6000
	s_mov_b32 m0, s31
	v_lshl_add_u64 v[6:7], v[226:227], 0, s[0:1]
	global_load_lds_dwordx4 v5, s[28:29]
	s_add_i32 s31, s31, 0x8000
	s_mov_b32 m0, s31
	s_nop 0
	global_load_lds_dwordx4 v[6:7], off
	s_waitcnt vmcnt(0) lgkmcnt(0)
	s_barrier
	s_add_i32 s45, s45, 2
	s_branch .LBB0_1463

.LBB0_1476:
	s_cmp_lt_u32 s63, 2
	s_cbranch_scc1 .Lhb_orig
	s_or_b64 s[98:99], s[0:1], s[96:97]
	s_cbranch_scc1 .Lhb_orig
	v_cmp_eq_f32_e64 s[18:19], s73, v222
	s_cmp_lg_u64 s[18:19], 0
	s_cbranch_scc1 .Lhb_full
	s_lshl_b32 s30, s20, 13
	v_add_u32_e32 v8, s30, v169
	v_add_u32_e32 v3, s30, v193
	ds_read_b128 v[10:13], v8
	ds_read_b128 v[14:17], v8 offset:512
	ds_read_b128 v[174:177], v8 offset:2048
	ds_read_b128 v[178:181], v8 offset:2560
	ds_read_b128 v[182:185], v8 offset:4096
	ds_read_b128 v[186:189], v8 offset:4608
	ds_read_b128 v[228:231], v8 offset:6144
	ds_read_b128 v[232:235], v8 offset:6656
	v_cmp_eq_f32_e64 s[18:19], s73, v222
	s_mov_b64 s[20:21], 0
	s_nop 0
	v_cndmask_b32_e64 v7, -v222, v204, s[18:19]
	v_add_f32_e32 v82, v7, v9
	v_add_f32_e32 v50, v7, v4
	v_mov_b32_e32 v83, v82
	v_mov_b64_e32 v[84:85], v[82:83]
	v_mov_b64_e32 v[86:87], v[82:83]
	v_mov_b64_e32 v[88:89], v[82:83]
	v_mov_b64_e32 v[90:91], v[82:83]
	v_mov_b64_e32 v[92:93], v[82:83]
	v_mov_b64_e32 v[94:95], v[82:83]
	v_mov_b64_e32 v[96:97], v[82:83]
	v_mov_b32_e32 v51, v50
	v_mov_b64_e32 v[52:53], v[50:51]
	s_waitcnt lgkmcnt(7)
	v_mfma_f32_32x32x16_bf16 v[98:113], v[10:13], v[114:117], v[82:97]
	ds_read_b128 v[10:13], v8 offset:8192
	v_mov_b64_e32 v[54:55], v[50:51]
	v_mov_b64_e32 v[56:57], v[50:51]
	v_mov_b64_e32 v[58:59], v[50:51]
	v_mov_b64_e32 v[60:61], v[50:51]
	v_mov_b64_e32 v[62:63], v[50:51]
	v_mov_b64_e32 v[64:65], v[50:51]
	s_waitcnt lgkmcnt(7)
	v_mfma_f32_32x32x16_bf16 v[82:97], v[14:17], v[114:117], v[82:97]
	ds_read_b128 v[14:17], v8 offset:8704
	s_waitcnt lgkmcnt(7)
	v_mfma_f32_32x32x16_bf16 v[98:113], v[174:177], v[118:121], v[98:113]
	ds_read_b128 v[174:177], v8 offset:10240
	s_waitcnt lgkmcnt(7)
	v_mfma_f32_32x32x16_bf16 v[82:97], v[178:181], v[118:121], v[82:97]
	ds_read_b128 v[178:181], v8 offset:10752
	s_waitcnt lgkmcnt(7)
	v_mfma_f32_32x32x16_bf16 v[98:113], v[182:185], v[122:125], v[98:113]
	ds_read_b128 v[182:185], v8 offset:12288
	s_waitcnt lgkmcnt(7)
	v_mfma_f32_32x32x16_bf16 v[82:97], v[186:189], v[122:125], v[82:97]
	ds_read_b128 v[186:189], v8 offset:12800
	s_waitcnt lgkmcnt(7)
	v_mfma_f32_32x32x16_bf16 v[98:113], v[228:231], v[126:129], v[98:113]
	ds_read_b128 v[228:231], v8 offset:14336
	s_waitcnt lgkmcnt(7)
	v_mfma_f32_32x32x16_bf16 v[82:97], v[232:235], v[126:129], v[82:97]
	ds_read_b128 v[232:235], v8 offset:14848
	s_waitcnt lgkmcnt(7)
	v_mfma_f32_32x32x16_bf16 v[66:81], v[10:13], v[114:117], v[50:65]
	ds_read_b64_tr_b16 v[10:11], v3 offset:32768
	ds_read_b64_tr_b16 v[12:13], v3 offset:33280
	s_waitcnt lgkmcnt(8)
	v_mfma_f32_32x32x16_bf16 v[50:65], v[14:17], v[114:117], v[50:65]
	ds_read_b64_tr_b16 v[14:15], v3 offset:36864
	ds_read_b64_tr_b16 v[16:17], v3 offset:37376
	s_waitcnt lgkmcnt(9)
	v_mfma_f32_32x32x16_bf16 v[66:81], v[174:177], v[118:121], v[66:81]
	ds_read_b64_tr_b16 v[174:175], v3 offset:33792
	ds_read_b64_tr_b16 v[176:177], v3 offset:34304
	v_exp_f32_e32 v98, v98
	v_exp_f32_e32 v99, v99
	v_exp_f32_e32 v100, v100
	v_exp_f32_e32 v101, v101
	v_exp_f32_e32 v102, v102
	s_waitcnt lgkmcnt(10)
	v_mfma_f32_32x32x16_bf16 v[50:65], v[178:181], v[118:121], v[50:65]
	ds_read_b64_tr_b16 v[178:179], v3 offset:37888
	ds_read_b64_tr_b16 v[180:181], v3 offset:38400
	v_exp_f32_e32 v103, v103
	v_exp_f32_e32 v104, v104
	v_exp_f32_e32 v105, v105
	v_cvt_pk_bf16_f32 v236, v98, v99
	v_cvt_pk_bf16_f32 v237, v100, v101
	v_cvt_pk_bf16_f32 v238, v102, v103
	v_cvt_pk_bf16_f32 v239, v104, v105
	s_waitcnt lgkmcnt(11)
	v_mfma_f32_32x32x16_bf16 v[66:81], v[182:185], v[122:125], v[66:81]
	ds_read_b64_tr_b16 v[182:183], v3 offset:34816
	ds_read_b64_tr_b16 v[184:185], v3 offset:35328
	v_exp_f32_e32 v106, v106
	v_exp_f32_e32 v107, v107
	v_exp_f32_e32 v108, v108
	v_exp_f32_e32 v109, v109
	v_exp_f32_e32 v110, v110
	s_waitcnt lgkmcnt(12)
	v_mfma_f32_32x32x16_bf16 v[50:65], v[186:189], v[122:125], v[50:65]
	ds_read_b64_tr_b16 v[186:187], v3 offset:38912
	ds_read_b64_tr_b16 v[188:189], v3 offset:39424
	v_exp_f32_e32 v111, v111
	v_exp_f32_e32 v112, v112
	v_exp_f32_e32 v113, v113
	v_cvt_pk_bf16_f32 v240, v106, v107
	v_cvt_pk_bf16_f32 v241, v108, v109
	v_cvt_pk_bf16_f32 v242, v110, v111
	v_cvt_pk_bf16_f32 v243, v112, v113
	s_waitcnt lgkmcnt(13)
	v_mfma_f32_32x32x16_bf16 v[66:81], v[228:231], v[126:129], v[66:81]
	ds_read_b64_tr_b16 v[228:229], v3 offset:35840
	ds_read_b64_tr_b16 v[230:231], v3 offset:36352
	v_exp_f32_e32 v82, v82
	v_exp_f32_e32 v83, v83
	v_exp_f32_e32 v84, v84
	v_exp_f32_e32 v85, v85
	v_exp_f32_e32 v86, v86
	s_waitcnt lgkmcnt(14)
	v_mfma_f32_32x32x16_bf16 v[50:65], v[232:235], v[126:129], v[50:65]
	s_waitcnt lgkmcnt(13)
	ds_read_b64_tr_b16 v[232:233], v3 offset:39936
	ds_read_b64_tr_b16 v[234:235], v3 offset:40448
	v_exp_f32_e32 v87, v87
	v_exp_f32_e32 v88, v88
	v_exp_f32_e32 v89, v89
	v_cvt_pk_bf16_f32 v244, v82, v83
	v_cvt_pk_bf16_f32 v245, v84, v85
	v_cvt_pk_bf16_f32 v246, v86, v87
	v_cvt_pk_bf16_f32 v247, v88, v89
	s_waitcnt lgkmcnt(14)
	v_mfma_f32_32x32x16_bf16 v[34:49], v[236:239], v[10:13], v[34:49]
	s_waitcnt lgkmcnt(13)
	ds_read_b64_tr_b16 v[10:11], v3 offset:40960
	ds_read_b64_tr_b16 v[12:13], v3 offset:41472
	v_exp_f32_e32 v90, v90
	v_exp_f32_e32 v91, v91
	v_exp_f32_e32 v92, v92
	v_exp_f32_e32 v93, v93
	v_exp_f32_e32 v94, v94
	s_waitcnt lgkmcnt(14)
	v_mfma_f32_32x32x16_bf16 v[18:33], v[236:239], v[14:17], v[18:33]
	s_waitcnt lgkmcnt(13)
	ds_read_b64_tr_b16 v[14:15], v3 offset:45056
	ds_read_b64_tr_b16 v[16:17], v3 offset:45568
	v_exp_f32_e32 v95, v95
	v_exp_f32_e32 v96, v96
	v_exp_f32_e32 v97, v97
	v_cvt_pk_bf16_f32 v248, v90, v91
	v_cvt_pk_bf16_f32 v249, v92, v93
	v_cvt_pk_bf16_f32 v250, v94, v95
	v_cvt_pk_bf16_f32 v251, v96, v97
	s_waitcnt lgkmcnt(14)
	v_mfma_f32_32x32x16_bf16 v[34:49], v[240:243], v[174:177], v[34:49]
	s_waitcnt lgkmcnt(13)
	ds_read_b64_tr_b16 v[174:175], v3 offset:41984
	ds_read_b64_tr_b16 v[176:177], v3 offset:42496
	v_exp_f32_e32 v66, v66
	v_exp_f32_e32 v67, v67
	v_exp_f32_e32 v68, v68
	v_exp_f32_e32 v69, v69
	v_exp_f32_e32 v70, v70
	s_waitcnt lgkmcnt(14)
	v_mfma_f32_32x32x16_bf16 v[18:33], v[240:243], v[178:181], v[18:33]
	s_waitcnt lgkmcnt(13)
	ds_read_b64_tr_b16 v[178:179], v3 offset:46080
	ds_read_b64_tr_b16 v[180:181], v3 offset:46592
	v_exp_f32_e32 v71, v71
	v_exp_f32_e32 v72, v72
	v_exp_f32_e32 v73, v73
	v_cvt_pk_bf16_f32 v236, v66, v67
	v_cvt_pk_bf16_f32 v237, v68, v69
	v_cvt_pk_bf16_f32 v238, v70, v71
	v_cvt_pk_bf16_f32 v239, v72, v73
	s_waitcnt lgkmcnt(14)
	v_mfma_f32_32x32x16_bf16 v[34:49], v[244:247], v[182:185], v[34:49]
	s_waitcnt lgkmcnt(13)
	ds_read_b64_tr_b16 v[182:183], v3 offset:43008
	ds_read_b64_tr_b16 v[184:185], v3 offset:43520
	v_exp_f32_e32 v74, v74
	v_exp_f32_e32 v75, v75
	v_exp_f32_e32 v76, v76
	v_exp_f32_e32 v77, v77
	v_exp_f32_e32 v78, v78
	s_waitcnt lgkmcnt(14)
	v_mfma_f32_32x32x16_bf16 v[18:33], v[244:247], v[186:189], v[18:33]
	s_waitcnt lgkmcnt(13)
	ds_read_b64_tr_b16 v[186:187], v3 offset:47104
	ds_read_b64_tr_b16 v[188:189], v3 offset:47616
	v_exp_f32_e32 v79, v79
	v_exp_f32_e32 v80, v80
	v_exp_f32_e32 v81, v81
	v_cvt_pk_bf16_f32 v240, v74, v75
	v_cvt_pk_bf16_f32 v241, v76, v77
	v_cvt_pk_bf16_f32 v242, v78, v79
	v_cvt_pk_bf16_f32 v243, v80, v81
	s_waitcnt lgkmcnt(14)
	v_mfma_f32_32x32x16_bf16 v[34:49], v[248:251], v[228:231], v[34:49]
	s_waitcnt lgkmcnt(13)
	ds_read_b64_tr_b16 v[228:229], v3 offset:44032
	ds_read_b64_tr_b16 v[230:231], v3 offset:44544
	v_exp_f32_e32 v50, v50
	v_exp_f32_e32 v51, v51
	v_exp_f32_e32 v52, v52
	v_exp_f32_e32 v53, v53
	v_exp_f32_e32 v54, v54
	s_waitcnt lgkmcnt(14)
	v_mfma_f32_32x32x16_bf16 v[18:33], v[248:251], v[232:235], v[18:33]
	s_waitcnt lgkmcnt(13)
	ds_read_b64_tr_b16 v[232:233], v3 offset:48128
	ds_read_b64_tr_b16 v[234:235], v3 offset:48640
	v_exp_f32_e32 v55, v55
	v_exp_f32_e32 v56, v56
	v_exp_f32_e32 v57, v57
	v_cvt_pk_bf16_f32 v244, v50, v51
	v_cvt_pk_bf16_f32 v245, v52, v53
	v_cvt_pk_bf16_f32 v246, v54, v55
	v_cvt_pk_bf16_f32 v247, v56, v57
	s_waitcnt lgkmcnt(14)
	v_mfma_f32_32x32x16_bf16 v[34:49], v[236:239], v[10:13], v[34:49]
	v_exp_f32_e32 v58, v58
	v_exp_f32_e32 v59, v59
	v_exp_f32_e32 v60, v60
	v_exp_f32_e32 v61, v61
	v_exp_f32_e32 v62, v62
	s_waitcnt lgkmcnt(12)
	v_mfma_f32_32x32x16_bf16 v[18:33], v[236:239], v[14:17], v[18:33]
	v_exp_f32_e32 v63, v63
	v_exp_f32_e32 v64, v64
	v_exp_f32_e32 v65, v65
	v_cvt_pk_bf16_f32 v248, v58, v59
	v_cvt_pk_bf16_f32 v249, v60, v61
	v_cvt_pk_bf16_f32 v250, v62, v63
	v_cvt_pk_bf16_f32 v251, v64, v65
	s_waitcnt lgkmcnt(10)
	v_mfma_f32_32x32x16_bf16 v[34:49], v[240:243], v[174:177], v[34:49]
	v_pk_add_f32 v[4:5], v[98:99], v[100:101]
	v_pk_add_f32 v[6:7], v[82:83], v[84:85]
	v_pk_add_f32 v[4:5], v[4:5], v[102:103]
	v_pk_add_f32 v[6:7], v[6:7], v[86:87]
	v_pk_add_f32 v[4:5], v[4:5], v[104:105]
	v_pk_add_f32 v[6:7], v[6:7], v[88:89]
	v_pk_add_f32 v[4:5], v[4:5], v[106:107]
	v_pk_add_f32 v[6:7], v[6:7], v[90:91]
	v_pk_add_f32 v[4:5], v[4:5], v[108:109]
	v_pk_add_f32 v[6:7], v[6:7], v[92:93]
	s_waitcnt lgkmcnt(8)
	v_mfma_f32_32x32x16_bf16 v[18:33], v[240:243], v[178:181], v[18:33]
	v_pk_add_f32 v[4:5], v[4:5], v[110:111]
	v_pk_add_f32 v[6:7], v[6:7], v[94:95]
	v_pk_add_f32 v[4:5], v[4:5], v[112:113]
	v_pk_add_f32 v[6:7], v[6:7], v[96:97]
	v_add_f32_e32 v6, v6, v7
	v_add_f32_e32 v4, v4, v5
	v_add_f32_e32 v4, v6, v4
	v_mov_b32_e32 v5, v4
	v_add_f32_e32 v225, v225, v4
	v_pk_add_f32 v[4:5], v[66:67], v[68:69]
	s_waitcnt lgkmcnt(6)
	v_mfma_f32_32x32x16_bf16 v[34:49], v[244:247], v[182:185], v[34:49]
	v_pk_add_f32 v[6:7], v[50:51], v[52:53]
	v_pk_add_f32 v[4:5], v[4:5], v[70:71]
	v_pk_add_f32 v[6:7], v[6:7], v[54:55]
	v_pk_add_f32 v[4:5], v[4:5], v[72:73]
	v_pk_add_f32 v[6:7], v[6:7], v[56:57]
	v_pk_add_f32 v[4:5], v[4:5], v[74:75]
	v_pk_add_f32 v[6:7], v[6:7], v[58:59]
	v_pk_add_f32 v[4:5], v[4:5], v[76:77]
	v_pk_add_f32 v[6:7], v[6:7], v[60:61]
	v_pk_add_f32 v[4:5], v[4:5], v[78:79]
	s_waitcnt lgkmcnt(4)
	v_mfma_f32_32x32x16_bf16 v[18:33], v[244:247], v[186:189], v[18:33]
	v_pk_add_f32 v[6:7], v[6:7], v[62:63]
	v_pk_add_f32 v[4:5], v[4:5], v[80:81]
	v_pk_add_f32 v[6:7], v[6:7], v[64:65]
	v_add_f32_e32 v6, v6, v7
	v_add_f32_e32 v4, v4, v5
	v_add_f32_e32 v4, v6, v4
	v_add_f32_e32 v225, v225, v4
	s_waitcnt lgkmcnt(2)
	v_mfma_f32_32x32x16_bf16 v[34:49], v[248:251], v[228:231], v[34:49]
	s_waitcnt lgkmcnt(0)
	v_mfma_f32_32x32x16_bf16 v[18:33], v[248:251], v[232:235], v[18:33]
	s_mov_b32 s30, 0x437f0000
	v_cmp_nge_f32_e32 vcc, s30, v5
	v_cmp_nge_f32_e64 s[98:99], s30, v4
	s_mov_b64 s[28:29], 0
	s_mov_b64 s[0:1], 0
	s_or_b64 s[98:99], vcc, s[98:99]
	s_cbranch_scc0 .LBB0_1492
	v_max3_f32 v5, v98, v99, v100
	v_max3_f32 v6, v106, v107, v108
	v_max3_f32 v9, v82, v83, v84
	v_max3_f32 v227, v90, v91, v92
	v_max3_f32 v5, v5, v101, v102
	v_max3_f32 v6, v6, v109, v110
	v_max3_f32 v9, v9, v85, v86
	v_max3_f32 v227, v227, v93, v94
	v_max3_f32 v5, v5, v103, v104
	v_max3_f32 v6, v6, v111, v112
	v_max3_f32 v9, v9, v87, v88
	v_max3_f32 v227, v227, v95, v96
	v_max3_f32 v5, v5, v105, v113
	v_max3_f32 v9, v9, v89, v97
	v_max3_f32 v5, v5, v6, v9
	v_max_f32_e32 v5, v5, v227
	v_mov_b32_e32 v6, v5
	s_nop 1
	v_permlane32_swap_b32_e32 v5, v6
	v_max_f32_e32 v5, v5, v6
	v_log_f32_e32 v5, v5
	s_nop 0
	v_cmp_lt_f32_e32 vcc, s74, v5
	s_and_b64 s[28:29], s[18:19], vcc
	v_cmp_lt_f32_e32 vcc, s75, v5
	s_or_b64 s[28:29], vcc, s[28:29]
	s_nop 0
	v_cndmask_b32_e64 v252, 0, v5, s[28:29]
	s_cselect_b64 s[28:29], -1, 0
	v_max3_f32 v5, v66, v67, v68
	v_max3_f32 v6, v74, v75, v76
	v_max3_f32 v9, v50, v51, v52
	v_max3_f32 v227, v58, v59, v60
	v_max3_f32 v5, v5, v69, v70
	v_max3_f32 v6, v6, v77, v78
	v_max3_f32 v9, v9, v53, v54
	v_max3_f32 v227, v227, v61, v62
	v_max3_f32 v5, v5, v71, v72
	v_max3_f32 v6, v6, v79, v80
	v_max3_f32 v9, v9, v55, v56
	v_max3_f32 v227, v227, v63, v64
	v_max3_f32 v5, v5, v73, v81
	v_max3_f32 v9, v9, v57, v65
	v_max3_f32 v5, v5, v6, v9
	v_max_f32_e32 v5, v5, v227
	v_mov_b32_e32 v6, v5
	s_nop 1
	v_permlane32_swap_b32_e32 v5, v6
	v_max_f32_e32 v5, v5, v6
	v_log_f32_e32 v5, v5
	s_nop 0
	v_cmp_lt_f32_e32 vcc, s74, v5
	s_and_b64 s[0:1], s[18:19], vcc
	v_cmp_lt_f32_e32 vcc, s75, v5
	s_or_b64 s[0:1], vcc, s[0:1]
	s_nop 0
	v_cndmask_b32_e64 v101, 0, v5, s[0:1]
	s_cselect_b64 s[0:1], -1, 0
	v_mov_b32_e32 v228, v252
	s_branch .LBB0_1492
